# GQA job: static s_setprio 1 for waves 0-3 instead (flips removed)
# baseline (speedup 1.0000x reference)
; DI int opaque_tid() { int t = threadIdx.x; asm volatile("" : "+v"(t)); return t; }
; template <int kind>
; __device__ void attn_job(const Params& p, int layer, int idx, char* smem) {
;     ...
;   const int tid = opaque_tid(), lane = tid & 63, w = __builtin_amdgcn_readfirstlane(tid >> 6), tq = lane & 31, hh = lane >> 5;
;   int b, qtok, qcol, ocol, kcol, vcol, nlat = 0, lat0 = 0, R0 = 0, hN = 0;
;   int qrow_l = 0, qc = 0, k0 = 0, r0A = 0, r0l = 0;
;   if (kind == 0) {
;     b = idx >> 5; const int kvh = (idx >> 4) & 1, qt = idx & 15;
;     const int head = kvh * 2 + (w >> 2);
;     qtok = b * SEQ + qt * 128 + (w & 3) * 32 + tq; qcol = GQ + head * 64; ocol = 512 + head * 64;
;     kcol = GK + kvh * 64; vcol = GV + kvh * 64; nlat = 32; lat0 = b * SEQ;
.LBB0_518:
	s_andn2_b64 vcc, exec, s[0:1]
	s_cbranch_vccnz .LBB0_529
	v_readfirstlane_b32 s100, v234
	s_nop 0
	s_bitcmp1_b32 s100, 8
	s_cbranch_scc1 .Lgqa_prio_skip
	s_setprio 1
